# combined + PV waves at static s_setprio 1 for the whole attention block
# baseline (speedup 1.0000x reference)
; __device__ __forceinline__ int v_rd_base(int lane) { return ((lane & 3) << 3) | (((lane >> 2) & 3) << 6) | (((lane >> 4) & 1) << 5) | (((lane >> 5) & 1) << 8); }
; #define A2_LOADT(t) do { const size_t ro_ = (size_t)((t) * 64 + sr) * D + sc; \
;         sk0 = att::load8(c.K + ro_); sk1 = att::load8(c.K + ro_ + 32 * D); sv00 = att::load8(c.V0 + ro_); sv01 = att::load8(c.V0 + ro_ + 32 * D); sv10 = att::load8(c.V1 + ro_); sv11 = att::load8(c.V1 + ro_ + 32 * D); } while (0)
; #define A2_WRITET(buf) do { char* kd_ = lds + L_K + (buf) * SHM_K; char* vd_ = lds + L_V + (buf) * 2 * SHM_V; \
;         *(bf16x8*)(kd_ + kws) = sk0; *(bf16x8*)(kd_ + kws + 32 * 256) = sk1; *(bf16x8*)(vd_ + vst0) = sv00; *(bf16x8*)(vd_ + vst1) = sv01; *(bf16x8*)(vd_ + SHM_V + vst0) = sv10; *(bf16x8*)(vd_ + SHM_V + vst1) = sv11; } while (0)
; __device__ __forceinline__ void attn2_block(const Blk& c, char* lds) {
;     ...
;     } else {
;         asm volatile("s_waitcnt vmcnt(0)" ::: "memory"); A2_WRITET(0); __syncthreads();
;         f32x16 o[8];
; #pragma unroll
;         for (int d_ = 0; d_ < 8; ++d_) o[d_] = f32x16{};
;         const int vbase = (int)(uintptr_t)(lds + L_V) + att::v_rd_base(lane);
;         for (int s = 0; s <= NT; ++s) {
;             if (s + 1 < NT) A2_LOADT(s + 1);
.LBB0_542:
	s_setprio 1
	v_lshlrev_b32_e32 v4, 3, v225
	v_lshlrev_b32_e32 v2, 4, v225
	v_lshlrev_b32_e32 v5, 1, v225
	v_and_b32_e32 v4, 0x118, v4
	s_cmp_lg_u32 0, -1
	v_add_u32_e32 v230, s16, v2
	v_and_b32_e32 v2, 0xc0, v2
	v_and_or_b32 v4, v5, 32, v4
	s_cselect_b32 s2, 0, 0
	v_add3_u32 v231, v2, s2, v4
	v_lshl_or_b32 v212, v222, 1, v212
	s_waitcnt vmcnt(0)
	s_barrier
	s_add_i32 m0, s100, 0x14000
	s_mov_b64 s[10:11], 0x4000
	global_load_lds_dwordx4 v[164:165], off
	global_load_lds_dwordx4 v[166:167], off offset:1024
	s_mov_b32 m0, s100
	v_lshl_add_u64 v[164:165], v[164:165], 0, s[10:11]
	global_load_lds_dwordx4 v[168:169], off
	s_add_i32 m0, s100, 0x380
	v_lshl_add_u64 v[166:167], v[166:167], 0, s[10:11]
	global_load_lds_dwordx4 v[168:169], off offset:128
	s_add_i32 m0, s100, 0x4000
	v_lshl_add_u64 v[168:169], v[168:169], 0, s[10:11]
	global_load_lds_dwordx4 v[170:171], off
	s_add_i32 m0, s100, 0x4380
	s_nop 0
	global_load_lds_dwordx4 v[170:171], off offset:128
	v_lshl_add_u64 v[170:171], v[170:171], 0, s[10:11]
	v_mov_b32_e32 v16, v3
	v_mov_b32_e32 v17, v3
	s_lshl_b32 s2, s30, 8
	v_mov_b32_e32 v2, v3
	v_mov_b32_e32 v4, v3
	v_mov_b32_e32 v5, v3
	v_mov_b32_e32 v6, v3
	v_mov_b32_e32 v7, v3
	v_mov_b32_e32 v8, v3
	v_mov_b32_e32 v9, v3
	v_mov_b32_e32 v10, v3
	v_mov_b32_e32 v11, v3
	v_mov_b32_e32 v12, v3
	v_mov_b32_e32 v13, v3
	v_mov_b32_e32 v14, v3
	v_mov_b32_e32 v15, v3
	v_mov_b64_e32 v[130:131], v[16:17]
	v_mov_b64_e32 v[114:115], v[16:17]
	v_mov_b64_e32 v[98:99], v[16:17]
	v_mov_b64_e32 v[82:83], v[16:17]
	v_mov_b64_e32 v[66:67], v[16:17]
	v_mov_b64_e32 v[50:51], v[16:17]
	v_mov_b64_e32 v[34:35], v[16:17]
	s_and_b32 s2, s2, 0x1fc000
	v_mov_b32_e32 v215, v213
	v_mov_b64_e32 v[128:129], v[14:15]
	v_mov_b64_e32 v[126:127], v[12:13]
	v_mov_b64_e32 v[124:125], v[10:11]
	v_mov_b64_e32 v[122:123], v[8:9]
	v_mov_b64_e32 v[120:121], v[6:7]
	v_mov_b64_e32 v[118:119], v[4:5]
	v_mov_b64_e32 v[116:117], v[2:3]
	v_mov_b64_e32 v[112:113], v[14:15]
	v_mov_b64_e32 v[110:111], v[12:13]
	v_mov_b64_e32 v[108:109], v[10:11]
	v_mov_b64_e32 v[106:107], v[8:9]
	v_mov_b64_e32 v[104:105], v[6:7]
	v_mov_b64_e32 v[102:103], v[4:5]
	v_mov_b64_e32 v[100:101], v[2:3]
	v_mov_b64_e32 v[96:97], v[14:15]
	v_mov_b64_e32 v[94:95], v[12:13]
	v_mov_b64_e32 v[92:93], v[10:11]
	v_mov_b64_e32 v[90:91], v[8:9]
	v_mov_b64_e32 v[88:89], v[6:7]
	v_mov_b64_e32 v[86:87], v[4:5]
	v_mov_b64_e32 v[84:85], v[2:3]
	v_mov_b64_e32 v[80:81], v[14:15]
	v_mov_b64_e32 v[78:79], v[12:13]
	v_mov_b64_e32 v[76:77], v[10:11]
	v_mov_b64_e32 v[74:75], v[8:9]
	v_mov_b64_e32 v[72:73], v[6:7]
	v_mov_b64_e32 v[70:71], v[4:5]
	v_mov_b64_e32 v[68:69], v[2:3]
	v_mov_b64_e32 v[64:65], v[14:15]
	v_mov_b64_e32 v[62:63], v[12:13]
	v_mov_b64_e32 v[60:61], v[10:11]
	v_mov_b64_e32 v[58:59], v[8:9]
	v_mov_b64_e32 v[56:57], v[6:7]
	v_mov_b64_e32 v[54:55], v[4:5]
	v_mov_b64_e32 v[52:53], v[2:3]
	v_mov_b64_e32 v[48:49], v[14:15]
	v_mov_b64_e32 v[46:47], v[12:13]
	v_mov_b64_e32 v[44:45], v[10:11]
	v_mov_b64_e32 v[42:43], v[8:9]
	v_mov_b64_e32 v[40:41], v[6:7]
	v_mov_b64_e32 v[38:39], v[4:5]
	v_mov_b64_e32 v[36:37], v[2:3]
	v_mov_b64_e32 v[32:33], v[14:15]
	v_mov_b64_e32 v[30:31], v[12:13]
	v_mov_b64_e32 v[28:29], v[10:11]
	v_mov_b64_e32 v[26:27], v[8:9]
	v_mov_b64_e32 v[24:25], v[6:7]
	v_mov_b64_e32 v[22:23], v[4:5]
	v_mov_b64_e32 v[20:21], v[2:3]
	v_mov_b64_e32 v[18:19], v[16:17]
	v_add_u32_e32 v212, s17, v216
	s_add_u32 s83, s2, 0x8000
	v_lshl_add_u64 v[218:219], s[46:47], 0, v[214:215]
	v_lshl_add_u64 v[220:221], s[58:59], 0, v[214:215]
	s_mov_b32 s84, 2
	s_mov_b64 s[2:3], 0
	v_mov_b64_e32 v[16:17], v[14:15]
	v_mov_b64_e32 v[14:15], v[12:13]
	v_mov_b64_e32 v[12:13], v[10:11]
	v_mov_b64_e32 v[10:11], v[8:9]
	v_mov_b64_e32 v[8:9], v[6:7]
	v_mov_b64_e32 v[6:7], v[4:5]
	v_mov_b64_e32 v[4:5], v[2:3]
	s_waitcnt vmcnt(0)
	s_waitcnt lgkmcnt(0)
	s_barrier
	s_branch .LBB0_544

; __device__ __forceinline__ int crow(int r, int hi) { return (r & 3) + 8 * (r >> 2) + 4 * hi; }
; __device__ __forceinline__ void attn2_block(const Blk& c, char* lds) {
;     ...
;         __syncthreads();
;         float rli[16];
; #pragma unroll
;         for (int r = 0; r < 16; ++r) rli[r] = __builtin_amdgcn_rcpf(LBb[att::crow(r, hi)]);
; #pragma unroll
;         for (int hf = 0; hf < 2; ++hf) { float* Ow = (hf ? c.O1 : c.O0) + (size_t)(g * 32) * D;
; #pragma unroll
;             for (int r = 0; r < 16; ++r) { const int orow = att::crow(r, hi);
; #pragma unroll
;                 for (int d0 = 0; d0 < 4; ++d0) Ow[(size_t)orow * D + d0 * 32 + r32] = o[hf * 4 + d0][r] * rli[r]; } }
.LBB0_550:
	s_setprio 0
	v_add_u32_e32 v2, s65, v216
	s_barrier
	s_waitcnt vmcnt(5)
	ds_read_b128 v[156:159], v2
	s_waitcnt vmcnt(4)
	ds_read_b128 v[160:163], v2 offset:32
	s_lshl_b32 s2, s30, 9
	s_add_u32 s4, s60, s2
	s_addc_u32 s5, s61, 0
	s_waitcnt vmcnt(3) lgkmcnt(1)
	v_rcp_f32_e32 v164, v156
	v_rcp_f32_e32 v165, v157
	v_rcp_f32_e32 v166, v158
	v_rcp_f32_e32 v167, v159
	ds_read_b128 v[156:159], v2 offset:64
	s_add_u32 s2, s62, s2
	s_waitcnt vmcnt(2) lgkmcnt(1)
	v_rcp_f32_e32 v168, v160
	v_rcp_f32_e32 v169, v161
	v_rcp_f32_e32 v170, v162
	v_rcp_f32_e32 v171, v163
	ds_read_b128 v[160:163], v2 offset:96
	s_addc_u32 s3, s63, 0
	s_lshl_b32 s10, s82, 14
	s_add_u32 s4, s4, s10
	s_addc_u32 s5, s5, 0
	v_lshlrev_b32_e32 v2, 2, v211
	s_waitcnt vmcnt(1) lgkmcnt(1)
	v_rcp_f32_e32 v172, v156
	v_rcp_f32_e32 v173, v157
	v_rcp_f32_e32 v174, v158
	v_rcp_f32_e32 v175, v159
	v_lshlrev_b32_e32 v156, 11, v226
	v_lshl_add_u64 v[158:159], s[4:5], 0, v[2:3]
	v_mov_b32_e32 v157, v3
	s_waitcnt vmcnt(0) lgkmcnt(0)
	v_rcp_f32_e32 v176, v160
	v_rcp_f32_e32 v177, v161
	v_lshl_add_u64 v[160:161], v[158:159], 0, v[156:157]
	v_mul_f32_e32 v68, v68, v164
	global_store_dword v[160:161], v68, off offset:384
	v_mul_f32_e32 v68, v117, v165
	global_store_dword v[160:161], v68, off offset:512
	v_mul_f32_e32 v68, v101, v165
	global_store_dword v[160:161], v68, off offset:640
	v_mul_f32_e32 v68, v85, v165
	global_store_dword v[160:161], v68, off offset:768
	v_mul_f32_e32 v68, v69, v165
	global_store_dword v[160:161], v68, off offset:896
	v_mul_f32_e32 v68, v118, v166
	global_store_dword v[160:161], v68, off offset:1024
	v_mul_f32_e32 v68, v102, v166
	global_store_dword v[160:161], v68, off offset:1152
	v_mul_f32_e32 v68, v86, v166
	global_store_dword v[160:161], v68, off offset:1280
	v_mul_f32_e32 v68, v70, v166
	global_store_dword v[160:161], v68, off offset:1408
	v_mul_f32_e32 v68, v119, v167
	global_store_dword v[160:161], v68, off offset:1536
	v_mul_f32_e32 v68, v103, v167
	global_store_dword v[160:161], v68, off offset:1664
	v_mul_f32_e32 v68, v87, v167
	global_store_dword v[160:161], v68, off offset:1792
	v_mul_f32_e32 v68, v71, v167
	v_mul_f32_e32 v84, v84, v164
	global_store_dword v[160:161], v68, off offset:1920
	v_or_b32_e32 v68, 0x1000, v156
	v_mov_b32_e32 v69, v3
	global_store_dword v[160:161], v84, off offset:256
	v_lshl_add_u64 v[70:71], v[158:159], 0, v[68:69]
	v_mul_f32_e32 v84, v120, v168
	global_store_dword v[70:71], v84, off
	v_mul_f32_e32 v84, v104, v168
	global_store_dword v[70:71], v84, off offset:128
	v_mul_f32_e32 v84, v88, v168
	v_mul_f32_e32 v72, v72, v168
	global_store_dword v[70:71], v84, off offset:256
	global_store_dword v[70:71], v72, off offset:384
	v_or_b32_e32 v70, 0x1200, v156
	v_mov_b32_e32 v71, v3
	v_lshl_add_u64 v[84:85], v[158:159], 0, v[70:71]
	v_mul_f32_e32 v72, v121, v169
	global_store_dword v[84:85], v72, off
	v_mul_f32_e32 v72, v105, v169
	global_store_dword v[84:85], v72, off offset:128
	v_mul_f32_e32 v72, v89, v169
	global_store_dword v[84:85], v72, off offset:256
	v_mul_f32_e32 v72, v73, v169
	global_store_dword v[84:85], v72, off offset:384
	v_or_b32_e32 v72, 0x1400, v156
	v_mov_b32_e32 v73, v3
	v_lshl_add_u64 v[84:85], v[158:159], 0, v[72:73]
	v_mul_f32_e32 v86, v122, v170
	global_store_dword v[84:85], v86, off
	v_mul_f32_e32 v86, v106, v170
	global_store_dword v[84:85], v86, off offset:128
	v_mul_f32_e32 v86, v90, v170
	v_mul_f32_e32 v74, v74, v170
	global_store_dword v[84:85], v86, off offset:256
	global_store_dword v[84:85], v74, off offset:384
	v_or_b32_e32 v84, 0x1600, v156
	v_mov_b32_e32 v85, v3
	v_lshl_add_u64 v[86:87], v[158:159], 0, v[84:85]
	v_mul_f32_e32 v74, v123, v171
	global_store_dword v[86:87], v74, off
	v_mul_f32_e32 v74, v107, v171
	global_store_dword v[86:87], v74, off offset:128
	v_mul_f32_e32 v74, v91, v171
	global_store_dword v[86:87], v74, off offset:256
	v_mul_f32_e32 v74, v75, v171
	global_store_dword v[86:87], v74, off offset:384
	v_or_b32_e32 v74, 0x2000, v156
	v_mov_b32_e32 v75, v3
	v_lshl_add_u64 v[86:87], v[158:159], 0, v[74:75]
	v_mul_f32_e32 v88, v124, v172
	global_store_dword v[86:87], v88, off
	v_mul_f32_e32 v88, v108, v172
	global_store_dword v[86:87], v88, off offset:128
	v_mul_f32_e32 v88, v92, v172
	v_mul_f32_e32 v76, v76, v172
	global_store_dword v[86:87], v88, off offset:256
	global_store_dword v[86:87], v76, off offset:384
	v_or_b32_e32 v86, 0x2200, v156
	v_mov_b32_e32 v87, v3
	v_lshl_add_u64 v[88:89], v[158:159], 0, v[86:87]
	v_mul_f32_e32 v76, v125, v173
	global_store_dword v[88:89], v76, off
	v_mul_f32_e32 v76, v109, v173
	global_store_dword v[88:89], v76, off offset:128
	v_mul_f32_e32 v76, v93, v173
	global_store_dword v[88:89], v76, off offset:256
	v_mul_f32_e32 v76, v77, v173
	global_store_dword v[88:89], v76, off offset:384
	v_or_b32_e32 v76, 0x2400, v156
	v_mov_b32_e32 v77, v3
	v_lshl_add_u64 v[88:89], v[158:159], 0, v[76:77]
	v_mul_f32_e32 v90, v126, v174
	global_store_dword v[88:89], v90, off
	v_mul_f32_e32 v90, v110, v174
	global_store_dword v[88:89], v90, off offset:128
	v_mul_f32_e32 v90, v94, v174
	v_mul_f32_e32 v78, v78, v174
	global_store_dword v[88:89], v90, off offset:256
	global_store_dword v[88:89], v78, off offset:384
	v_or_b32_e32 v88, 0x2600, v156
	v_mov_b32_e32 v89, v3
	v_lshl_add_u64 v[90:91], v[158:159], 0, v[88:89]
	v_mul_f32_e32 v78, v127, v175
	global_store_dword v[90:91], v78, off
	v_mul_f32_e32 v78, v111, v175
	global_store_dword v[90:91], v78, off offset:128
	v_mul_f32_e32 v78, v95, v175
	global_store_dword v[90:91], v78, off offset:256
	v_mul_f32_e32 v78, v79, v175
	global_store_dword v[90:91], v78, off offset:384
	v_or_b32_e32 v78, 0x3000, v156
; __device__ __forceinline__ int crow(int r, int hi) { return (r & 3) + 8 * (r >> 2) + 4 * hi; }
; __device__ __forceinline__ void attn2_block(const Blk& c, char* lds) {
;     ...
; #pragma unroll
;         for (int hf = 0; hf < 2; ++hf) { float* Ow = (hf ? c.O1 : c.O0) + (size_t)(g * 32) * D;
; #pragma unroll
;             for (int r = 0; r < 16; ++r) { const int orow = att::crow(r, hi);
; #pragma unroll
;                 for (int d0 = 0; d0 < 4; ++d0) Ow[(size_t)orow * D + d0 * 32 + r32] = o[hf * 4 + d0][r] * rli[r]; } }
	v_mov_b32_e32 v79, v3
	v_lshl_add_u64 v[90:91], v[158:159], 0, v[78:79]
	v_mul_f32_e32 v92, v128, v176
	global_store_dword v[90:91], v92, off
	v_mul_f32_e32 v92, v112, v176
	global_store_dword v[90:91], v92, off offset:128
	v_mul_f32_e32 v92, v96, v176
	v_mul_f32_e32 v80, v80, v176
	global_store_dword v[90:91], v92, off offset:256
	global_store_dword v[90:91], v80, off offset:384
	v_or_b32_e32 v90, 0x3200, v156
	v_mov_b32_e32 v91, v3
	v_lshl_add_u64 v[92:93], v[158:159], 0, v[90:91]
	v_mul_f32_e32 v80, v129, v177
	v_rcp_f32_e32 v162, v162
	global_store_dword v[92:93], v80, off
	v_mul_f32_e32 v80, v113, v177
	global_store_dword v[92:93], v80, off offset:128
	v_mul_f32_e32 v80, v97, v177
	global_store_dword v[92:93], v80, off offset:256
	v_mul_f32_e32 v80, v81, v177
	global_store_dword v[92:93], v80, off offset:384
	v_or_b32_e32 v80, 0x3400, v156
	v_mov_b32_e32 v81, v3
	v_rcp_f32_e32 v163, v163
	v_lshl_add_u64 v[92:93], v[158:159], 0, v[80:81]
	v_mul_f32_e32 v94, v130, v162
	global_store_dword v[92:93], v94, off
	v_mul_f32_e32 v94, v114, v162
	global_store_dword v[92:93], v94, off offset:128
	v_mul_f32_e32 v94, v98, v162
	v_mul_f32_e32 v82, v82, v162
	global_store_dword v[92:93], v94, off offset:256
	global_store_dword v[92:93], v82, off offset:384
	v_or_b32_e32 v92, 0x3600, v156
	v_mov_b32_e32 v93, v3
	v_lshl_add_u64 v[94:95], v[158:159], 0, v[92:93]
	v_mul_f32_e32 v82, v131, v163
	global_store_dword v[94:95], v82, off
	v_mul_f32_e32 v82, v115, v163
	global_store_dword v[94:95], v82, off offset:128
	v_mul_f32_e32 v82, v99, v163
	s_add_u32 s2, s2, s10
	global_store_dword v[94:95], v82, off offset:256
	v_mul_f32_e32 v82, v83, v163
	s_addc_u32 s3, s3, 0
	global_store_dword v[94:95], v82, off offset:384
	v_lshl_add_u64 v[82:83], s[2:3], 0, v[2:3]
	v_lshl_add_u64 v[94:95], v[82:83], 0, v[156:157]
	v_mul_f32_e32 v2, v52, v164
	global_store_dword v[94:95], v2, off
	v_mul_f32_e32 v2, v36, v164
	global_store_dword v[94:95], v2, off offset:128
	v_mul_f32_e32 v2, v20, v164
	global_store_dword v[94:95], v2, off offset:256
	v_mul_f32_e32 v2, v4, v164
	global_store_dword v[94:95], v2, off offset:384
	v_mul_f32_e32 v2, v53, v165
	global_store_dword v[94:95], v2, off offset:512
	v_mul_f32_e32 v2, v37, v165
	global_store_dword v[94:95], v2, off offset:640
	v_mul_f32_e32 v2, v21, v165
	global_store_dword v[94:95], v2, off offset:768
	v_mul_f32_e32 v2, v5, v165
	global_store_dword v[94:95], v2, off offset:896
	v_mul_f32_e32 v2, v54, v166
	global_store_dword v[94:95], v2, off offset:1024
	v_mul_f32_e32 v2, v38, v166
	global_store_dword v[94:95], v2, off offset:1152
	v_mul_f32_e32 v2, v22, v166
	global_store_dword v[94:95], v2, off offset:1280
	v_mul_f32_e32 v2, v6, v166
	global_store_dword v[94:95], v2, off offset:1408
	v_mul_f32_e32 v2, v55, v167
	global_store_dword v[94:95], v2, off offset:1536
	v_mul_f32_e32 v2, v39, v167
	global_store_dword v[94:95], v2, off offset:1664
	v_mul_f32_e32 v2, v23, v167
	global_store_dword v[94:95], v2, off offset:1792
	v_mul_f32_e32 v2, v7, v167
	global_store_dword v[94:95], v2, off offset:1920
	v_lshl_add_u64 v[4:5], v[82:83], 0, v[68:69]
	v_mul_f32_e32 v2, v56, v168
	global_store_dword v[4:5], v2, off
	v_mul_f32_e32 v2, v40, v168
	global_store_dword v[4:5], v2, off offset:128
	v_mul_f32_e32 v2, v24, v168
	global_store_dword v[4:5], v2, off offset:256
	v_mul_f32_e32 v2, v8, v168
	global_store_dword v[4:5], v2, off offset:384
	v_lshl_add_u64 v[4:5], v[82:83], 0, v[70:71]
	v_mul_f32_e32 v2, v57, v169
	global_store_dword v[4:5], v2, off
	v_mul_f32_e32 v2, v41, v169
	global_store_dword v[4:5], v2, off offset:128
	v_mul_f32_e32 v2, v25, v169
	global_store_dword v[4:5], v2, off offset:256
; __device__ __forceinline__ int crow(int r, int hi) { return (r & 3) + 8 * (r >> 2) + 4 * hi; }
; __device__ __forceinline__ void attn2_block(const Blk& c, char* lds) {
;     ...
; #pragma unroll
;         for (int hf = 0; hf < 2; ++hf) { float* Ow = (hf ? c.O1 : c.O0) + (size_t)(g * 32) * D;
; #pragma unroll
;             for (int r = 0; r < 16; ++r) { const int orow = att::crow(r, hi);
; #pragma unroll
;                 for (int d0 = 0; d0 < 4; ++d0) Ow[(size_t)orow * D + d0 * 32 + r32] = o[hf * 4 + d0][r] * rli[r]; } }
	v_mul_f32_e32 v2, v9, v169
	global_store_dword v[4:5], v2, off offset:384
	v_lshl_add_u64 v[4:5], v[82:83], 0, v[72:73]
	v_mul_f32_e32 v2, v58, v170
	global_store_dword v[4:5], v2, off
	v_mul_f32_e32 v2, v42, v170
	global_store_dword v[4:5], v2, off offset:128
	v_mul_f32_e32 v2, v26, v170
	global_store_dword v[4:5], v2, off offset:256
	v_mul_f32_e32 v2, v10, v170
	global_store_dword v[4:5], v2, off offset:384
	v_lshl_add_u64 v[4:5], v[82:83], 0, v[84:85]
	v_mul_f32_e32 v2, v59, v171
	global_store_dword v[4:5], v2, off
	v_mul_f32_e32 v2, v43, v171
	global_store_dword v[4:5], v2, off offset:128
	v_mul_f32_e32 v2, v27, v171
	global_store_dword v[4:5], v2, off offset:256
	v_mul_f32_e32 v2, v11, v171
	global_store_dword v[4:5], v2, off offset:384
	v_lshl_add_u64 v[4:5], v[82:83], 0, v[74:75]
	v_mul_f32_e32 v2, v60, v172
	global_store_dword v[4:5], v2, off
	v_mul_f32_e32 v2, v44, v172
	global_store_dword v[4:5], v2, off offset:128
	v_mul_f32_e32 v2, v28, v172
	global_store_dword v[4:5], v2, off offset:256
	v_mul_f32_e32 v2, v12, v172
	global_store_dword v[4:5], v2, off offset:384
	v_lshl_add_u64 v[4:5], v[82:83], 0, v[86:87]
	v_mul_f32_e32 v2, v61, v173
	global_store_dword v[4:5], v2, off
	v_mul_f32_e32 v2, v45, v173
	global_store_dword v[4:5], v2, off offset:128
	v_mul_f32_e32 v2, v29, v173
	global_store_dword v[4:5], v2, off offset:256
	v_mul_f32_e32 v2, v13, v173
	global_store_dword v[4:5], v2, off offset:384
	v_lshl_add_u64 v[4:5], v[82:83], 0, v[76:77]
	v_mul_f32_e32 v2, v62, v174
	global_store_dword v[4:5], v2, off
	v_mul_f32_e32 v2, v46, v174
	global_store_dword v[4:5], v2, off offset:128
	v_mul_f32_e32 v2, v30, v174
	global_store_dword v[4:5], v2, off offset:256
	v_mul_f32_e32 v2, v14, v174
	global_store_dword v[4:5], v2, off offset:384
	v_lshl_add_u64 v[4:5], v[82:83], 0, v[88:89]
	v_mul_f32_e32 v2, v63, v175
	global_store_dword v[4:5], v2, off
	v_mul_f32_e32 v2, v47, v175
	global_store_dword v[4:5], v2, off offset:128
	v_mul_f32_e32 v2, v31, v175
	global_store_dword v[4:5], v2, off offset:256
	v_mul_f32_e32 v2, v15, v175
	global_store_dword v[4:5], v2, off offset:384
	v_lshl_add_u64 v[4:5], v[82:83], 0, v[78:79]
	v_mul_f32_e32 v2, v64, v176
	global_store_dword v[4:5], v2, off
	v_mul_f32_e32 v2, v48, v176
	global_store_dword v[4:5], v2, off offset:128
	v_mul_f32_e32 v2, v32, v176
	global_store_dword v[4:5], v2, off offset:256
	v_mul_f32_e32 v2, v16, v176
	global_store_dword v[4:5], v2, off offset:384
	v_lshl_add_u64 v[4:5], v[82:83], 0, v[90:91]
	v_mul_f32_e32 v2, v65, v177
	global_store_dword v[4:5], v2, off
	v_mul_f32_e32 v2, v49, v177
	global_store_dword v[4:5], v2, off offset:128
	v_mul_f32_e32 v2, v33, v177
	global_store_dword v[4:5], v2, off offset:256
	v_mul_f32_e32 v2, v17, v177
	global_store_dword v[4:5], v2, off offset:384
	v_lshl_add_u64 v[4:5], v[82:83], 0, v[80:81]
	v_mul_f32_e32 v2, v66, v162
	global_store_dword v[4:5], v2, off
	v_mul_f32_e32 v2, v50, v162
	global_store_dword v[4:5], v2, off offset:128
	v_mul_f32_e32 v2, v34, v162
	global_store_dword v[4:5], v2, off offset:256
	v_mul_f32_e32 v2, v18, v162
	global_store_dword v[4:5], v2, off offset:384
	v_lshl_add_u64 v[4:5], v[82:83], 0, v[92:93]
	v_mul_f32_e32 v2, v67, v163
	global_store_dword v[4:5], v2, off
	v_mul_f32_e32 v2, v51, v163
	global_store_dword v[4:5], v2, off offset:128
	v_mul_f32_e32 v2, v35, v163
	v_mul_f32_e32 v116, v116, v164
	v_mul_f32_e32 v100, v100, v164
	global_store_dword v[4:5], v2, off offset:256
	v_mul_f32_e32 v2, v19, v163
	global_store_dword v[160:161], v116, off
	global_store_dword v[160:161], v100, off offset:128
	global_store_dword v[4:5], v2, off offset:384
	s_branch .LBB0_539
